# ml_out epilogue loop: unrolled x4 with two register sets, next iteration's 12 loads issued before the current iteration's gate math
# baseline (speedup 1.0000x reference)
.LBB0_923:
	v_mov_b32_e32 v204, v16
	v_mov_b32_e32 v205, v17
	global_load_dwordx4 v[32:35], v[12:13], off offset:-192
	global_load_dwordx4 v[8:11], v[12:13], off offset:-128
	global_load_dwordx2 v[36:37], v[14:15], off offset:-64
	global_load_dwordx2 v[26:27], v[14:15], off offset:-32
	global_load_dwordx2 v[22:23], v[14:15], off
	global_load_dwordx2 v[18:19], v[14:15], off offset:32
	global_load_dwordx4 v[4:7], v[12:13], off offset:-64
	global_load_dwordx4 v[0:3], v[12:13], off
	global_load_dwordx2 v[38:39], v[204:205], off offset:-64
	global_load_dwordx2 v[28:29], v[204:205], off offset:-32
	global_load_dwordx2 v[24:25], v[204:205], off
	global_load_dwordx2 v[20:21], v[204:205], off offset:32
	v_lshl_add_u64 v[14:15], v[14:15], 0, s[20:21]
	s_mov_b64 s[10:11], 0x100
	v_lshl_add_u64 v[12:13], v[12:13], 0, s[10:11]
	v_lshl_add_u64 v[204:205], v[204:205], 0, s[20:21]
	global_load_dwordx4 v[134:137], v[12:13], off offset:-192
	global_load_dwordx4 v[138:141], v[12:13], off offset:-128
	global_load_dwordx2 v[172:173], v[14:15], off offset:-64
	global_load_dwordx2 v[174:175], v[14:15], off offset:-32
	global_load_dwordx2 v[176:177], v[14:15], off
	global_load_dwordx2 v[178:179], v[14:15], off offset:32
	global_load_dwordx4 v[142:145], v[12:13], off offset:-64
	global_load_dwordx4 v[146:149], v[12:13], off
	global_load_dwordx2 v[180:181], v[204:205], off offset:-64
	global_load_dwordx2 v[182:183], v[204:205], off offset:-32
	global_load_dwordx2 v[184:185], v[204:205], off
	global_load_dwordx2 v[202:203], v[204:205], off offset:32
	v_lshl_add_u64 v[14:15], v[14:15], 0, s[20:21]
	s_mov_b64 s[10:11], 0x100
	v_lshl_add_u64 v[12:13], v[12:13], 0, s[10:11]
	v_lshl_add_u64 v[204:205], v[204:205], 0, s[20:21]
	s_waitcnt vmcnt(21)
	v_lshlrev_b32_e32 v31, 16, v36
	v_mul_f32_e32 v31, 0xbfb8aa3b, v31
	v_exp_f32_e32 v31, v31
	s_waitcnt vmcnt(15)
	v_lshlrev_b32_e32 v41, 16, v38
	v_mul_f32_e32 v41, v30, v41
	v_mul_f32_e32 v32, v32, v41
	v_add_f32_e32 v31, 1.0, v31
	v_and_b32_e32 v38, 0xffff0000, v38
	v_and_b32_e32 v36, 0xffff0000, v36
	v_lshlrev_b32_e32 v40, 16, v37
	v_rcp_f32_e32 v31, v31
	s_nop 0
	v_mul_f32_e32 v31, v32, v31
	v_mul_f32_e32 v32, v30, v38
	v_mul_f32_e32 v32, v33, v32
	v_mul_f32_e32 v33, 0xbfb8aa3b, v36
	v_exp_f32_e32 v33, v33
	v_lshlrev_b32_e32 v42, 16, v39
	v_and_b32_e32 v37, 0xffff0000, v37
	v_and_b32_e32 v39, 0xffff0000, v39
	v_add_f32_e32 v33, 1.0, v33
	v_rcp_f32_e32 v33, v33
	s_nop 0
	v_mul_f32_e32 v32, v32, v33
	v_mul_f32_e32 v33, 0xbfb8aa3b, v40
	v_exp_f32_e32 v33, v33
	v_cvt_pk_bf16_f32 v32, v31, v32
	v_mul_f32_e32 v31, v30, v42
	v_mul_f32_e32 v31, v34, v31
	v_add_f32_e32 v33, 1.0, v33
	s_nop 0
	v_rcp_f32_e32 v33, v33
	v_mul_f32_e32 v34, 0xbfb8aa3b, v37
	v_exp_f32_e32 v34, v34
	v_mul_f32_e32 v31, v31, v33
	v_mul_f32_e32 v33, v30, v39
	v_mul_f32_e32 v33, v35, v33
	v_add_f32_e32 v34, 1.0, v34
	s_nop 0
	v_rcp_f32_e32 v34, v34
	s_nop 0
	v_mul_f32_e32 v33, v33, v34
	v_cvt_pk_bf16_f32 v33, v31, v33
	v_lshlrev_b32_e32 v31, 16, v26
	v_mul_f32_e32 v31, 0xbfb8aa3b, v31
	v_exp_f32_e32 v31, v31
	global_store_dwordx2 v[16:17], v[32:33], off offset:-64
	s_waitcnt vmcnt(15)
	v_lshlrev_b32_e32 v33, 16, v28
	v_mul_f32_e32 v33, v30, v33
	v_add_f32_e32 v31, 1.0, v31
	v_mul_f32_e32 v8, v8, v33
	v_and_b32_e32 v26, 0xffff0000, v26
	v_mul_f32_e32 v26, 0xbfb8aa3b, v26
	v_exp_f32_e32 v26, v26
	v_and_b32_e32 v28, 0xffff0000, v28
	v_mul_f32_e32 v28, v30, v28
	v_add_f32_e32 v26, 1.0, v26
	v_rcp_f32_e32 v31, v31
	v_mul_f32_e32 v9, v9, v28
	v_mul_f32_e32 v8, v8, v31
	v_lshlrev_b32_e32 v34, 16, v29
	v_lshlrev_b32_e32 v32, 16, v27
	v_and_b32_e32 v29, 0xffff0000, v29
	v_rcp_f32_e32 v26, v26
	s_nop 0
	v_mul_f32_e32 v9, v9, v26
	v_cvt_pk_bf16_f32 v8, v8, v9
	v_mul_f32_e32 v9, v30, v34
	v_mul_f32_e32 v9, v10, v9
	v_mul_f32_e32 v10, 0xbfb8aa3b, v32
	v_exp_f32_e32 v10, v10
	v_and_b32_e32 v27, 0xffff0000, v27
	v_add_f32_e32 v10, 1.0, v10
	s_nop 0
	v_rcp_f32_e32 v10, v10
	s_nop 0
	v_mul_f32_e32 v9, v9, v10
	v_mul_f32_e32 v10, v30, v29
	v_mul_f32_e32 v10, v11, v10
	v_mul_f32_e32 v11, 0xbfb8aa3b, v27
	v_exp_f32_e32 v11, v11
	s_nop 0
	v_add_f32_e32 v11, 1.0, v11
	s_nop 0
	v_rcp_f32_e32 v11, v11
	s_nop 0
	v_mul_f32_e32 v10, v10, v11
	v_cvt_pk_bf16_f32 v9, v9, v10
	global_store_dwordx2 v[16:17], v[8:9], off offset:-32
	v_lshlrev_b32_e32 v8, 16, v22
	v_mul_f32_e32 v8, 0xbfb8aa3b, v8
	v_exp_f32_e32 v8, v8
	v_and_b32_e32 v9, 0xffff0000, v22
	s_waitcnt vmcnt(15)
	v_lshlrev_b32_e32 v22, 16, v24
	v_mul_f32_e32 v22, v30, v22
	v_add_f32_e32 v8, 1.0, v8
	v_mul_f32_e32 v4, v4, v22
	v_lshlrev_b32_e32 v10, 16, v23
	v_and_b32_e32 v11, 0xffff0000, v23
	v_and_b32_e32 v23, 0xffff0000, v24
	v_rcp_f32_e32 v8, v8
	s_nop 0
	v_mul_f32_e32 v4, v4, v8
	v_mul_f32_e32 v8, v30, v23
	v_mul_f32_e32 v5, v5, v8
	v_mul_f32_e32 v8, 0xbfb8aa3b, v9
	v_exp_f32_e32 v8, v8
	v_lshlrev_b32_e32 v24, 16, v25
	v_and_b32_e32 v25, 0xffff0000, v25
	v_add_f32_e32 v8, 1.0, v8
	s_nop 0
	v_rcp_f32_e32 v8, v8
	s_nop 0
	v_mul_f32_e32 v5, v5, v8
	v_cvt_pk_bf16_f32 v4, v4, v5
	v_mul_f32_e32 v5, v30, v24
	v_mul_f32_e32 v5, v6, v5
	v_mul_f32_e32 v6, 0xbfb8aa3b, v10
	v_exp_f32_e32 v6, v6
	s_nop 0
	v_add_f32_e32 v6, 1.0, v6
	s_nop 0
	v_rcp_f32_e32 v6, v6
	s_nop 0
	v_mul_f32_e32 v5, v5, v6
	v_mul_f32_e32 v6, v30, v25
	v_mul_f32_e32 v6, v7, v6
	v_mul_f32_e32 v7, 0xbfb8aa3b, v11
	v_exp_f32_e32 v7, v7
	s_nop 0
	v_add_f32_e32 v7, 1.0, v7
	s_nop 0
	v_rcp_f32_e32 v7, v7
	s_nop 0
	v_mul_f32_e32 v6, v6, v7
	v_cvt_pk_bf16_f32 v5, v5, v6
	global_store_dwordx2 v[16:17], v[4:5], off
	v_lshlrev_b32_e32 v4, 16, v18
	v_mul_f32_e32 v4, 0xbfb8aa3b, v4
	v_exp_f32_e32 v4, v4
	s_waitcnt vmcnt(15)
	v_lshlrev_b32_e32 v8, 16, v20
	v_mul_f32_e32 v8, v30, v8
	v_mul_f32_e32 v0, v0, v8
	v_add_f32_e32 v4, 1.0, v4
	v_and_b32_e32 v5, 0xffff0000, v18
	v_lshlrev_b32_e32 v6, 16, v19
	v_and_b32_e32 v7, 0xffff0000, v19
	v_and_b32_e32 v9, 0xffff0000, v20
	v_lshlrev_b32_e32 v10, 16, v21
	v_and_b32_e32 v11, 0xffff0000, v21
	v_rcp_f32_e32 v4, v4
	s_nop 0
	v_mul_f32_e32 v0, v0, v4
	v_mul_f32_e32 v4, v30, v9
	v_mul_f32_e32 v1, v1, v4
	v_mul_f32_e32 v4, 0xbfb8aa3b, v5
	v_exp_f32_e32 v4, v4
	s_nop 0
	v_add_f32_e32 v4, 1.0, v4
	s_nop 0
	v_rcp_f32_e32 v4, v4
	s_nop 0
	v_mul_f32_e32 v1, v1, v4
	v_cvt_pk_bf16_f32 v0, v0, v1
	v_mul_f32_e32 v1, v30, v10
	v_mul_f32_e32 v1, v2, v1
	v_mul_f32_e32 v2, 0xbfb8aa3b, v6
	v_exp_f32_e32 v2, v2
	s_nop 0
	v_add_f32_e32 v2, 1.0, v2
	s_nop 0
	v_rcp_f32_e32 v2, v2
	s_nop 0
	v_mul_f32_e32 v1, v1, v2
	v_mul_f32_e32 v2, v30, v11
	v_mul_f32_e32 v2, v3, v2
	v_mul_f32_e32 v3, 0xbfb8aa3b, v7
	v_exp_f32_e32 v3, v3
	s_nop 0
	v_add_f32_e32 v3, 1.0, v3
	v_rcp_f32_e32 v3, v3
	s_nop 0
	v_mul_f32_e32 v2, v2, v3
	v_cvt_pk_bf16_f32 v1, v1, v2
	global_store_dwordx2 v[16:17], v[0:1], off offset:32
	v_lshl_add_u64 v[16:17], v[16:17], 0, s[20:21]
	global_load_dwordx4 v[32:35], v[12:13], off offset:-192
	global_load_dwordx4 v[8:11], v[12:13], off offset:-128
	global_load_dwordx2 v[36:37], v[14:15], off offset:-64
	global_load_dwordx2 v[26:27], v[14:15], off offset:-32
	global_load_dwordx2 v[22:23], v[14:15], off
	global_load_dwordx2 v[18:19], v[14:15], off offset:32
	global_load_dwordx4 v[4:7], v[12:13], off offset:-64
	global_load_dwordx4 v[0:3], v[12:13], off
	global_load_dwordx2 v[38:39], v[204:205], off offset:-64
	global_load_dwordx2 v[28:29], v[204:205], off offset:-32
	global_load_dwordx2 v[24:25], v[204:205], off
	global_load_dwordx2 v[20:21], v[204:205], off offset:32
	v_lshl_add_u64 v[14:15], v[14:15], 0, s[20:21]
	s_mov_b64 s[10:11], 0x100
	v_lshl_add_u64 v[12:13], v[12:13], 0, s[10:11]
	v_lshl_add_u64 v[204:205], v[204:205], 0, s[20:21]
	s_waitcnt vmcnt(25)
	v_lshlrev_b32_e32 v31, 16, v172
	v_mul_f32_e32 v31, 0xbfb8aa3b, v31
	v_exp_f32_e32 v31, v31
	s_waitcnt vmcnt(19)
	v_lshlrev_b32_e32 v41, 16, v180
	v_mul_f32_e32 v41, v30, v41
	v_mul_f32_e32 v134, v134, v41
	v_add_f32_e32 v31, 1.0, v31
	v_and_b32_e32 v180, 0xffff0000, v180
	v_and_b32_e32 v172, 0xffff0000, v172
	v_lshlrev_b32_e32 v40, 16, v173
	v_rcp_f32_e32 v31, v31
	s_nop 0
	v_mul_f32_e32 v31, v134, v31
	v_mul_f32_e32 v134, v30, v180
	v_mul_f32_e32 v134, v135, v134
	v_mul_f32_e32 v135, 0xbfb8aa3b, v172
	v_exp_f32_e32 v135, v135
	v_lshlrev_b32_e32 v42, 16, v181
	v_and_b32_e32 v173, 0xffff0000, v173
	v_and_b32_e32 v181, 0xffff0000, v181
	v_add_f32_e32 v135, 1.0, v135
	v_rcp_f32_e32 v135, v135
	s_nop 0
	v_mul_f32_e32 v134, v134, v135
	v_mul_f32_e32 v135, 0xbfb8aa3b, v40
	v_exp_f32_e32 v135, v135
	v_cvt_pk_bf16_f32 v134, v31, v134
	v_mul_f32_e32 v31, v30, v42
	v_mul_f32_e32 v31, v136, v31
	v_add_f32_e32 v135, 1.0, v135
	s_nop 0
	v_rcp_f32_e32 v135, v135
	v_mul_f32_e32 v136, 0xbfb8aa3b, v173
	v_exp_f32_e32 v136, v136
	v_mul_f32_e32 v31, v31, v135
	v_mul_f32_e32 v135, v30, v181
	v_mul_f32_e32 v135, v137, v135
	v_add_f32_e32 v136, 1.0, v136
	s_nop 0
	v_rcp_f32_e32 v136, v136
	s_nop 0
	v_mul_f32_e32 v135, v135, v136
	v_cvt_pk_bf16_f32 v135, v31, v135
	v_lshlrev_b32_e32 v31, 16, v174
	v_mul_f32_e32 v31, 0xbfb8aa3b, v31
	v_exp_f32_e32 v31, v31
	global_store_dwordx2 v[16:17], v[134:135], off offset:-64
	s_waitcnt vmcnt(19)
	v_lshlrev_b32_e32 v135, 16, v182
	v_mul_f32_e32 v135, v30, v135
	v_add_f32_e32 v31, 1.0, v31
	v_mul_f32_e32 v138, v138, v135
	v_and_b32_e32 v174, 0xffff0000, v174
	v_mul_f32_e32 v174, 0xbfb8aa3b, v174
	v_exp_f32_e32 v174, v174
	v_and_b32_e32 v182, 0xffff0000, v182
	v_mul_f32_e32 v182, v30, v182
	v_add_f32_e32 v174, 1.0, v174
	v_rcp_f32_e32 v31, v31
	v_mul_f32_e32 v139, v139, v182
	v_mul_f32_e32 v138, v138, v31
	v_lshlrev_b32_e32 v136, 16, v183
	v_lshlrev_b32_e32 v134, 16, v175
	v_and_b32_e32 v183, 0xffff0000, v183
	v_rcp_f32_e32 v174, v174
	s_nop 0
	v_mul_f32_e32 v139, v139, v174
	v_cvt_pk_bf16_f32 v138, v138, v139
	v_mul_f32_e32 v139, v30, v136
	v_mul_f32_e32 v139, v140, v139
	v_mul_f32_e32 v140, 0xbfb8aa3b, v134
	v_exp_f32_e32 v140, v140
	v_and_b32_e32 v175, 0xffff0000, v175
	v_add_f32_e32 v140, 1.0, v140
	s_nop 0
	v_rcp_f32_e32 v140, v140
	s_nop 0
	v_mul_f32_e32 v139, v139, v140
	v_mul_f32_e32 v140, v30, v183
	v_mul_f32_e32 v140, v141, v140
	v_mul_f32_e32 v141, 0xbfb8aa3b, v175
	v_exp_f32_e32 v141, v141
	s_nop 0
	v_add_f32_e32 v141, 1.0, v141
	s_nop 0
	v_rcp_f32_e32 v141, v141
	s_nop 0
	v_mul_f32_e32 v140, v140, v141
	v_cvt_pk_bf16_f32 v139, v139, v140
	global_store_dwordx2 v[16:17], v[138:139], off offset:-32
	v_lshlrev_b32_e32 v138, 16, v176
	v_mul_f32_e32 v138, 0xbfb8aa3b, v138
	v_exp_f32_e32 v138, v138
	v_and_b32_e32 v139, 0xffff0000, v176
	s_waitcnt vmcnt(19)
	v_lshlrev_b32_e32 v176, 16, v184
	v_mul_f32_e32 v176, v30, v176
	v_add_f32_e32 v138, 1.0, v138
	v_mul_f32_e32 v142, v142, v176
	v_lshlrev_b32_e32 v140, 16, v177
	v_and_b32_e32 v141, 0xffff0000, v177
	v_and_b32_e32 v177, 0xffff0000, v184
	v_rcp_f32_e32 v138, v138
	s_nop 0
	v_mul_f32_e32 v142, v142, v138
	v_mul_f32_e32 v138, v30, v177
	v_mul_f32_e32 v143, v143, v138
	v_mul_f32_e32 v138, 0xbfb8aa3b, v139
	v_exp_f32_e32 v138, v138
	v_lshlrev_b32_e32 v184, 16, v185
	v_and_b32_e32 v185, 0xffff0000, v185
	v_add_f32_e32 v138, 1.0, v138
	s_nop 0
	v_rcp_f32_e32 v138, v138
	s_nop 0
	v_mul_f32_e32 v143, v143, v138
	v_cvt_pk_bf16_f32 v142, v142, v143
	v_mul_f32_e32 v143, v30, v184
	v_mul_f32_e32 v143, v144, v143
	v_mul_f32_e32 v144, 0xbfb8aa3b, v140
	v_exp_f32_e32 v144, v144
	s_nop 0
	v_add_f32_e32 v144, 1.0, v144
	s_nop 0
	v_rcp_f32_e32 v144, v144
	s_nop 0
	v_mul_f32_e32 v143, v143, v144
	v_mul_f32_e32 v144, v30, v185
	v_mul_f32_e32 v144, v145, v144
	v_mul_f32_e32 v145, 0xbfb8aa3b, v141
	v_exp_f32_e32 v145, v145
	s_nop 0
	v_add_f32_e32 v145, 1.0, v145
	s_nop 0
	v_rcp_f32_e32 v145, v145
	s_nop 0
	v_mul_f32_e32 v144, v144, v145
	v_cvt_pk_bf16_f32 v143, v143, v144
	global_store_dwordx2 v[16:17], v[142:143], off
	v_lshlrev_b32_e32 v142, 16, v178
	v_mul_f32_e32 v142, 0xbfb8aa3b, v142
	v_exp_f32_e32 v142, v142
	s_waitcnt vmcnt(19)
	v_lshlrev_b32_e32 v138, 16, v202
	v_mul_f32_e32 v138, v30, v138
	v_mul_f32_e32 v146, v146, v138
	v_add_f32_e32 v142, 1.0, v142
	v_and_b32_e32 v143, 0xffff0000, v178
	v_lshlrev_b32_e32 v144, 16, v179
	v_and_b32_e32 v145, 0xffff0000, v179
	v_and_b32_e32 v139, 0xffff0000, v202
	v_lshlrev_b32_e32 v140, 16, v203
	v_and_b32_e32 v141, 0xffff0000, v203
	v_rcp_f32_e32 v142, v142
	s_nop 0
	v_mul_f32_e32 v146, v146, v142
	v_mul_f32_e32 v142, v30, v139
	v_mul_f32_e32 v147, v147, v142
	v_mul_f32_e32 v142, 0xbfb8aa3b, v143
	v_exp_f32_e32 v142, v142
	s_nop 0
	v_add_f32_e32 v142, 1.0, v142
	s_nop 0
	v_rcp_f32_e32 v142, v142
	s_nop 0
	v_mul_f32_e32 v147, v147, v142
	v_cvt_pk_bf16_f32 v146, v146, v147
	v_mul_f32_e32 v147, v30, v140
	v_mul_f32_e32 v147, v148, v147
	v_mul_f32_e32 v148, 0xbfb8aa3b, v144
	v_exp_f32_e32 v148, v148
	s_nop 0
	v_add_f32_e32 v148, 1.0, v148
	s_nop 0
	v_rcp_f32_e32 v148, v148
	s_nop 0
	v_mul_f32_e32 v147, v147, v148
	v_mul_f32_e32 v148, v30, v141
	v_mul_f32_e32 v148, v149, v148
	v_mul_f32_e32 v149, 0xbfb8aa3b, v145
	v_exp_f32_e32 v149, v149
	s_nop 0
	v_add_f32_e32 v149, 1.0, v149
	v_rcp_f32_e32 v149, v149
	s_nop 0
	v_mul_f32_e32 v148, v148, v149
	v_cvt_pk_bf16_f32 v147, v147, v148
	global_store_dwordx2 v[16:17], v[146:147], off offset:32
	v_lshl_add_u64 v[16:17], v[16:17], 0, s[20:21]
	global_load_dwordx4 v[134:137], v[12:13], off offset:-192
	global_load_dwordx4 v[138:141], v[12:13], off offset:-128
	global_load_dwordx2 v[172:173], v[14:15], off offset:-64
	global_load_dwordx2 v[174:175], v[14:15], off offset:-32
	global_load_dwordx2 v[176:177], v[14:15], off
	global_load_dwordx2 v[178:179], v[14:15], off offset:32
	global_load_dwordx4 v[142:145], v[12:13], off offset:-64
	global_load_dwordx4 v[146:149], v[12:13], off
	global_load_dwordx2 v[180:181], v[204:205], off offset:-64
	global_load_dwordx2 v[182:183], v[204:205], off offset:-32
	global_load_dwordx2 v[184:185], v[204:205], off
	global_load_dwordx2 v[202:203], v[204:205], off offset:32
	s_waitcnt vmcnt(25)
	v_lshlrev_b32_e32 v31, 16, v36
	v_mul_f32_e32 v31, 0xbfb8aa3b, v31
	v_exp_f32_e32 v31, v31
	s_waitcnt vmcnt(19)
	v_lshlrev_b32_e32 v41, 16, v38
	v_mul_f32_e32 v41, v30, v41
	v_mul_f32_e32 v32, v32, v41
	v_add_f32_e32 v31, 1.0, v31
	v_and_b32_e32 v38, 0xffff0000, v38
	v_and_b32_e32 v36, 0xffff0000, v36
	v_lshlrev_b32_e32 v40, 16, v37
	v_rcp_f32_e32 v31, v31
	s_nop 0
	v_mul_f32_e32 v31, v32, v31
	v_mul_f32_e32 v32, v30, v38
	v_mul_f32_e32 v32, v33, v32
	v_mul_f32_e32 v33, 0xbfb8aa3b, v36
	v_exp_f32_e32 v33, v33
	v_lshlrev_b32_e32 v42, 16, v39
	v_and_b32_e32 v37, 0xffff0000, v37
	v_and_b32_e32 v39, 0xffff0000, v39
	v_add_f32_e32 v33, 1.0, v33
	v_rcp_f32_e32 v33, v33
	s_nop 0
	v_mul_f32_e32 v32, v32, v33
	v_mul_f32_e32 v33, 0xbfb8aa3b, v40
	v_exp_f32_e32 v33, v33
	v_cvt_pk_bf16_f32 v32, v31, v32
	v_mul_f32_e32 v31, v30, v42
	v_mul_f32_e32 v31, v34, v31
	v_add_f32_e32 v33, 1.0, v33
	s_nop 0
	v_rcp_f32_e32 v33, v33
	v_mul_f32_e32 v34, 0xbfb8aa3b, v37
	v_exp_f32_e32 v34, v34
	v_mul_f32_e32 v31, v31, v33
	v_mul_f32_e32 v33, v30, v39
	v_mul_f32_e32 v33, v35, v33
	v_add_f32_e32 v34, 1.0, v34
	s_nop 0
	v_rcp_f32_e32 v34, v34
	s_nop 0
	v_mul_f32_e32 v33, v33, v34
	v_cvt_pk_bf16_f32 v33, v31, v33
	v_lshlrev_b32_e32 v31, 16, v26
	v_mul_f32_e32 v31, 0xbfb8aa3b, v31
	v_exp_f32_e32 v31, v31
	global_store_dwordx2 v[16:17], v[32:33], off offset:-64
	s_waitcnt vmcnt(19)
	v_lshlrev_b32_e32 v33, 16, v28
	v_mul_f32_e32 v33, v30, v33
	v_add_f32_e32 v31, 1.0, v31
	v_mul_f32_e32 v8, v8, v33
	v_and_b32_e32 v26, 0xffff0000, v26
	v_mul_f32_e32 v26, 0xbfb8aa3b, v26
	v_exp_f32_e32 v26, v26
	v_and_b32_e32 v28, 0xffff0000, v28
	v_mul_f32_e32 v28, v30, v28
	v_add_f32_e32 v26, 1.0, v26
	v_rcp_f32_e32 v31, v31
	v_mul_f32_e32 v9, v9, v28
	v_mul_f32_e32 v8, v8, v31
	v_lshlrev_b32_e32 v34, 16, v29
	v_lshlrev_b32_e32 v32, 16, v27
	v_and_b32_e32 v29, 0xffff0000, v29
	v_rcp_f32_e32 v26, v26
	s_nop 0
	v_mul_f32_e32 v9, v9, v26
	v_cvt_pk_bf16_f32 v8, v8, v9
	v_mul_f32_e32 v9, v30, v34
	v_mul_f32_e32 v9, v10, v9
	v_mul_f32_e32 v10, 0xbfb8aa3b, v32
	v_exp_f32_e32 v10, v10
	v_and_b32_e32 v27, 0xffff0000, v27
	v_add_f32_e32 v10, 1.0, v10
	s_nop 0
	v_rcp_f32_e32 v10, v10
	s_nop 0
	v_mul_f32_e32 v9, v9, v10
	v_mul_f32_e32 v10, v30, v29
	v_mul_f32_e32 v10, v11, v10
	v_mul_f32_e32 v11, 0xbfb8aa3b, v27
	v_exp_f32_e32 v11, v11
	s_nop 0
	v_add_f32_e32 v11, 1.0, v11
	s_nop 0
	v_rcp_f32_e32 v11, v11
	s_nop 0
	v_mul_f32_e32 v10, v10, v11
	v_cvt_pk_bf16_f32 v9, v9, v10
	global_store_dwordx2 v[16:17], v[8:9], off offset:-32
	v_lshlrev_b32_e32 v8, 16, v22
	v_mul_f32_e32 v8, 0xbfb8aa3b, v8
	v_exp_f32_e32 v8, v8
	v_and_b32_e32 v9, 0xffff0000, v22
	s_waitcnt vmcnt(19)
	v_lshlrev_b32_e32 v22, 16, v24
	v_mul_f32_e32 v22, v30, v22
	v_add_f32_e32 v8, 1.0, v8
	v_mul_f32_e32 v4, v4, v22
	v_lshlrev_b32_e32 v10, 16, v23
	v_and_b32_e32 v11, 0xffff0000, v23
	v_and_b32_e32 v23, 0xffff0000, v24
	v_rcp_f32_e32 v8, v8
	s_nop 0
	v_mul_f32_e32 v4, v4, v8
	v_mul_f32_e32 v8, v30, v23
	v_mul_f32_e32 v5, v5, v8
	v_mul_f32_e32 v8, 0xbfb8aa3b, v9
	v_exp_f32_e32 v8, v8
	v_lshlrev_b32_e32 v24, 16, v25
	v_and_b32_e32 v25, 0xffff0000, v25
	v_add_f32_e32 v8, 1.0, v8
	s_nop 0
	v_rcp_f32_e32 v8, v8
	s_nop 0
	v_mul_f32_e32 v5, v5, v8
	v_cvt_pk_bf16_f32 v4, v4, v5
	v_mul_f32_e32 v5, v30, v24
	v_mul_f32_e32 v5, v6, v5
	v_mul_f32_e32 v6, 0xbfb8aa3b, v10
	v_exp_f32_e32 v6, v6
	s_nop 0
	v_add_f32_e32 v6, 1.0, v6
	s_nop 0
	v_rcp_f32_e32 v6, v6
	s_nop 0
	v_mul_f32_e32 v5, v5, v6
	v_mul_f32_e32 v6, v30, v25
	v_mul_f32_e32 v6, v7, v6
	v_mul_f32_e32 v7, 0xbfb8aa3b, v11
	v_exp_f32_e32 v7, v7
	s_nop 0
	v_add_f32_e32 v7, 1.0, v7
	s_nop 0
	v_rcp_f32_e32 v7, v7
	s_nop 0
	v_mul_f32_e32 v6, v6, v7
	v_cvt_pk_bf16_f32 v5, v5, v6
	global_store_dwordx2 v[16:17], v[4:5], off
	v_lshlrev_b32_e32 v4, 16, v18
	v_mul_f32_e32 v4, 0xbfb8aa3b, v4
	v_exp_f32_e32 v4, v4
	s_waitcnt vmcnt(19)
	v_lshlrev_b32_e32 v8, 16, v20
	v_mul_f32_e32 v8, v30, v8
	v_mul_f32_e32 v0, v0, v8
	v_add_f32_e32 v4, 1.0, v4
	v_and_b32_e32 v5, 0xffff0000, v18
	v_lshlrev_b32_e32 v6, 16, v19
	v_and_b32_e32 v7, 0xffff0000, v19
	v_and_b32_e32 v9, 0xffff0000, v20
	v_lshlrev_b32_e32 v10, 16, v21
	v_and_b32_e32 v11, 0xffff0000, v21
	v_rcp_f32_e32 v4, v4
	s_nop 0
	v_mul_f32_e32 v0, v0, v4
	v_mul_f32_e32 v4, v30, v9
	v_mul_f32_e32 v1, v1, v4
	v_mul_f32_e32 v4, 0xbfb8aa3b, v5
	v_exp_f32_e32 v4, v4
	s_nop 0
	v_add_f32_e32 v4, 1.0, v4
	s_nop 0
	v_rcp_f32_e32 v4, v4
	s_nop 0
	v_mul_f32_e32 v1, v1, v4
	v_cvt_pk_bf16_f32 v0, v0, v1
	v_mul_f32_e32 v1, v30, v10
	v_mul_f32_e32 v1, v2, v1
	v_mul_f32_e32 v2, 0xbfb8aa3b, v6
	v_exp_f32_e32 v2, v2
	s_nop 0
	v_add_f32_e32 v2, 1.0, v2
	s_nop 0
	v_rcp_f32_e32 v2, v2
	s_nop 0
	v_mul_f32_e32 v1, v1, v2
	v_mul_f32_e32 v2, v30, v11
	v_mul_f32_e32 v2, v3, v2
	v_mul_f32_e32 v3, 0xbfb8aa3b, v7
	v_exp_f32_e32 v3, v3
	s_nop 0
	v_add_f32_e32 v3, 1.0, v3
	v_rcp_f32_e32 v3, v3
	s_nop 0
	v_mul_f32_e32 v2, v2, v3
	v_cvt_pk_bf16_f32 v1, v1, v2
	global_store_dwordx2 v[16:17], v[0:1], off offset:32
	v_lshl_add_u64 v[16:17], v[16:17], 0, s[20:21]
	s_waitcnt vmcnt(13)
	v_lshlrev_b32_e32 v31, 16, v172
	v_mul_f32_e32 v31, 0xbfb8aa3b, v31
	v_exp_f32_e32 v31, v31
	s_waitcnt vmcnt(7)
	v_lshlrev_b32_e32 v41, 16, v180
	v_mul_f32_e32 v41, v30, v41
	v_mul_f32_e32 v134, v134, v41
	v_add_f32_e32 v31, 1.0, v31
	v_and_b32_e32 v180, 0xffff0000, v180
	v_and_b32_e32 v172, 0xffff0000, v172
	v_lshlrev_b32_e32 v40, 16, v173
	v_rcp_f32_e32 v31, v31
	s_nop 0
	v_mul_f32_e32 v31, v134, v31
	v_mul_f32_e32 v134, v30, v180
	v_mul_f32_e32 v134, v135, v134
	v_mul_f32_e32 v135, 0xbfb8aa3b, v172
	v_exp_f32_e32 v135, v135
	v_lshlrev_b32_e32 v42, 16, v181
	v_and_b32_e32 v173, 0xffff0000, v173
	v_and_b32_e32 v181, 0xffff0000, v181
	v_add_f32_e32 v135, 1.0, v135
	v_rcp_f32_e32 v135, v135
	s_nop 0
	v_mul_f32_e32 v134, v134, v135
	v_mul_f32_e32 v135, 0xbfb8aa3b, v40
	v_exp_f32_e32 v135, v135
	v_cvt_pk_bf16_f32 v134, v31, v134
	v_mul_f32_e32 v31, v30, v42
	v_mul_f32_e32 v31, v136, v31
	v_add_f32_e32 v135, 1.0, v135
	s_nop 0
	v_rcp_f32_e32 v135, v135
	v_mul_f32_e32 v136, 0xbfb8aa3b, v173
	v_exp_f32_e32 v136, v136
	v_mul_f32_e32 v31, v31, v135
	v_mul_f32_e32 v135, v30, v181
	v_mul_f32_e32 v135, v137, v135
	v_add_f32_e32 v136, 1.0, v136
	s_nop 0
	v_rcp_f32_e32 v136, v136
	s_nop 0
	v_mul_f32_e32 v135, v135, v136
	v_cvt_pk_bf16_f32 v135, v31, v135
	v_lshlrev_b32_e32 v31, 16, v174
	v_mul_f32_e32 v31, 0xbfb8aa3b, v31
	v_exp_f32_e32 v31, v31
	global_store_dwordx2 v[16:17], v[134:135], off offset:-64
	s_waitcnt vmcnt(7)
	v_lshlrev_b32_e32 v135, 16, v182
	v_mul_f32_e32 v135, v30, v135
	v_add_f32_e32 v31, 1.0, v31
	v_mul_f32_e32 v138, v138, v135
	v_and_b32_e32 v174, 0xffff0000, v174
	v_mul_f32_e32 v174, 0xbfb8aa3b, v174
	v_exp_f32_e32 v174, v174
	v_and_b32_e32 v182, 0xffff0000, v182
	v_mul_f32_e32 v182, v30, v182
	v_add_f32_e32 v174, 1.0, v174
	v_rcp_f32_e32 v31, v31
	v_mul_f32_e32 v139, v139, v182
	v_mul_f32_e32 v138, v138, v31
	v_lshlrev_b32_e32 v136, 16, v183
	v_lshlrev_b32_e32 v134, 16, v175
	v_and_b32_e32 v183, 0xffff0000, v183
	v_rcp_f32_e32 v174, v174
	s_nop 0
	v_mul_f32_e32 v139, v139, v174
	v_cvt_pk_bf16_f32 v138, v138, v139
	v_mul_f32_e32 v139, v30, v136
	v_mul_f32_e32 v139, v140, v139
	v_mul_f32_e32 v140, 0xbfb8aa3b, v134
	v_exp_f32_e32 v140, v140
	v_and_b32_e32 v175, 0xffff0000, v175
	v_add_f32_e32 v140, 1.0, v140
	s_nop 0
	v_rcp_f32_e32 v140, v140
	s_nop 0
	v_mul_f32_e32 v139, v139, v140
	v_mul_f32_e32 v140, v30, v183
	v_mul_f32_e32 v140, v141, v140
	v_mul_f32_e32 v141, 0xbfb8aa3b, v175
	v_exp_f32_e32 v141, v141
	s_nop 0
	v_add_f32_e32 v141, 1.0, v141
	s_nop 0
	v_rcp_f32_e32 v141, v141
	s_nop 0
	v_mul_f32_e32 v140, v140, v141
	v_cvt_pk_bf16_f32 v139, v139, v140
	global_store_dwordx2 v[16:17], v[138:139], off offset:-32
	v_lshlrev_b32_e32 v138, 16, v176
	v_mul_f32_e32 v138, 0xbfb8aa3b, v138
	v_exp_f32_e32 v138, v138
	v_and_b32_e32 v139, 0xffff0000, v176
	s_waitcnt vmcnt(7)
	v_lshlrev_b32_e32 v176, 16, v184
	v_mul_f32_e32 v176, v30, v176
	v_add_f32_e32 v138, 1.0, v138
	v_mul_f32_e32 v142, v142, v176
	v_lshlrev_b32_e32 v140, 16, v177
	v_and_b32_e32 v141, 0xffff0000, v177
	v_and_b32_e32 v177, 0xffff0000, v184
	v_rcp_f32_e32 v138, v138
	s_nop 0
	v_mul_f32_e32 v142, v142, v138
	v_mul_f32_e32 v138, v30, v177
	v_mul_f32_e32 v143, v143, v138
	v_mul_f32_e32 v138, 0xbfb8aa3b, v139
	v_exp_f32_e32 v138, v138
	v_lshlrev_b32_e32 v184, 16, v185
	v_and_b32_e32 v185, 0xffff0000, v185
	v_add_f32_e32 v138, 1.0, v138
	s_nop 0
	v_rcp_f32_e32 v138, v138
	s_nop 0
	v_mul_f32_e32 v143, v143, v138
	v_cvt_pk_bf16_f32 v142, v142, v143
	v_mul_f32_e32 v143, v30, v184
	v_mul_f32_e32 v143, v144, v143
	v_mul_f32_e32 v144, 0xbfb8aa3b, v140
	v_exp_f32_e32 v144, v144
	s_nop 0
	v_add_f32_e32 v144, 1.0, v144
	s_nop 0
	v_rcp_f32_e32 v144, v144
	s_nop 0
	v_mul_f32_e32 v143, v143, v144
	v_mul_f32_e32 v144, v30, v185
	v_mul_f32_e32 v144, v145, v144
	v_mul_f32_e32 v145, 0xbfb8aa3b, v141
	v_exp_f32_e32 v145, v145
	s_nop 0
	v_add_f32_e32 v145, 1.0, v145
	s_nop 0
	v_rcp_f32_e32 v145, v145
	s_nop 0
	v_mul_f32_e32 v144, v144, v145
	v_cvt_pk_bf16_f32 v143, v143, v144
	global_store_dwordx2 v[16:17], v[142:143], off
	v_lshlrev_b32_e32 v142, 16, v178
	v_mul_f32_e32 v142, 0xbfb8aa3b, v142
	v_exp_f32_e32 v142, v142
	s_waitcnt vmcnt(7)
	v_lshlrev_b32_e32 v138, 16, v202
	v_mul_f32_e32 v138, v30, v138
	v_mul_f32_e32 v146, v146, v138
	v_add_f32_e32 v142, 1.0, v142
	v_and_b32_e32 v143, 0xffff0000, v178
	v_lshlrev_b32_e32 v144, 16, v179
	v_and_b32_e32 v145, 0xffff0000, v179
	v_and_b32_e32 v139, 0xffff0000, v202
	v_lshlrev_b32_e32 v140, 16, v203
	v_and_b32_e32 v141, 0xffff0000, v203
	v_rcp_f32_e32 v142, v142
	s_nop 0
	v_mul_f32_e32 v146, v146, v142
	v_mul_f32_e32 v142, v30, v139
	v_mul_f32_e32 v147, v147, v142
	v_mul_f32_e32 v142, 0xbfb8aa3b, v143
	v_exp_f32_e32 v142, v142
	s_nop 0
	v_add_f32_e32 v142, 1.0, v142
	s_nop 0
	v_rcp_f32_e32 v142, v142
	s_nop 0
	v_mul_f32_e32 v147, v147, v142
	v_cvt_pk_bf16_f32 v146, v146, v147
	v_mul_f32_e32 v147, v30, v140
	v_mul_f32_e32 v147, v148, v147
	v_mul_f32_e32 v148, 0xbfb8aa3b, v144
	v_exp_f32_e32 v148, v148
	s_nop 0
	v_add_f32_e32 v148, 1.0, v148
	s_nop 0
	v_rcp_f32_e32 v148, v148
	s_nop 0
	v_mul_f32_e32 v147, v147, v148
	v_mul_f32_e32 v148, v30, v141
	v_mul_f32_e32 v148, v149, v148
	v_mul_f32_e32 v149, 0xbfb8aa3b, v145
	v_exp_f32_e32 v149, v149
	s_nop 0
	v_add_f32_e32 v149, 1.0, v149
	v_rcp_f32_e32 v149, v149
	s_nop 0
	v_mul_f32_e32 v148, v148, v149
	v_cvt_pk_bf16_f32 v147, v147, v148
	global_store_dwordx2 v[16:17], v[146:147], off offset:32
	v_lshl_add_u64 v[16:17], v[16:17], 0, s[20:21]
	s_branch .LBB0_786
